# GLA walk compute segment: all LDS operand reads issued up front with counted waits, output and state MFMAs interleaved
# speedup vs baseline: 1.0157x; 1.0128x over previous
.LBB0_470:
	s_or_b64 exec, exec, s[14:15]
	s_waitcnt lgkmcnt(0)
	s_barrier
	s_and_b64 s[14:15], exec, s[64:65]
	s_or_b64 s[10:11], s[14:15], s[10:11]
	s_setprio 1
	v_and_b32_e32 v33, 32, v57
	s_movk_i32 s14, 0x90
	v_mad_u32_u24 v33, v33, s14, v175
	s_and_b64 vcc, exec, s[46:47]
	s_cbranch_vccz .Lgb_k1
	s_and_b64 vcc, exec, s[62:63]
	s_cbranch_vccnz .Lgb_m0k2
	ds_read_b128 v[188:191], v132
	ds_read_b128 v[84:87], v33 offset:23552
	ds_read_b128 v[88:91], v33 offset:25856
	ds_read_b128 v[192:195], v132 offset:64
	ds_read_b128 v[92:95], v33 offset:23616
	ds_read_b128 v[196:199], v33 offset:25920
	ds_read_b64_tr_b16 v[200:201], v133 offset:18432
	ds_read_b64_tr_b16 v[202:203], v133 offset:18752
	ds_read_b64_tr_b16 v[238:239], v140 offset:9216
	ds_read_b64_tr_b16 v[240:241], v140 offset:9792
	ds_read_b64_tr_b16 v[234:235], v134 offset:18432
	ds_read_b64_tr_b16 v[236:237], v134 offset:18752
	ds_read_b64_tr_b16 v[242:243], v141 offset:9216
	ds_read_b64_tr_b16 v[244:245], v141 offset:9792
	ds_read_b32 v204, v143 offset:32768
	v_lshlrev_b32_e32 v34, 16, v30
	v_and_b32_e32 v35, 0xffff0000, v30
	v_lshlrev_b32_e32 v96, 16, v31
	v_and_b32_e32 v97, 0xffff0000, v31
	v_lshlrev_b32_e32 v98, 16, v28
	v_and_b32_e32 v99, 0xffff0000, v28
	v_lshlrev_b32_e32 v100, 16, v29
	v_and_b32_e32 v101, 0xffff0000, v29
	v_add_u32_e32 v32, v32, v54
	v_mad_i64_i32 v[32:33], s[14:15], v32, s16, v[2:3]
	s_waitcnt lgkmcnt(12)
	v_mfma_f32_16x16x32_bf16 v[84:87], v[84:87], v[188:191], 0
	v_mfma_f32_16x16x32_bf16 v[88:91], v[88:91], v[188:191], 0
	s_waitcnt lgkmcnt(9)
	v_mfma_f32_16x16x32_bf16 v[84:87], v[92:95], v[192:195], v[84:87]
	v_mfma_f32_16x16x32_bf16 v[88:91], v[196:199], v[192:195], v[88:91]
	ds_read_b64_tr_b16 v[246:247], v135 offset:9248
	ds_read_b64_tr_b16 v[248:249], v135 offset:9824
	ds_read_b64_tr_b16 v[250:251], v136 offset:9248
	ds_read_b64_tr_b16 v[252:253], v136 offset:9824
	ds_read_b32 v205, v144 offset:32832
	s_movk_i32 s14, 0x90
	v_add_u32_e32 v57, 32, v57
	v_and_b32_e32 v28, 32, v57
	v_mad_u32_u24 v28, v28, s14, v71
	v_lshlrev_b32_e32 v29, 1, v114
	v_lshlrev_b32_e32 v30, 1, v142
	v_add3_u32 v30, v28, v30, v29
	v_lshlrev_b32_e32 v31, 1, v112
	v_add3_u32 v31, v28, v31, v29
	s_waitcnt lgkmcnt(10)
	v_mfma_f32_16x16x32_bf16 v[8:11], v[200:203], v[238:241], v[8:11]
	s_waitcnt lgkmcnt(6)
	v_mfma_f32_16x16x32_bf16 v[8:11], v[234:237], v[242:245], v[8:11]
	s_waitcnt lgkmcnt(3)
	v_mfma_f32_16x16x32_bf16 v[4:7], v[200:203], v[246:249], v[4:7]
	s_waitcnt lgkmcnt(1)
	v_mfma_f32_16x16x32_bf16 v[4:7], v[234:237], v[250:253], v[4:7]
	v_add_f32_e32 v34, v84, v34
	v_add_f32_e32 v35, v85, v35
	v_add_f32_e32 v96, v86, v96
	v_add_f32_e32 v97, v87, v97
	v_add_f32_e32 v98, v88, v98
	v_add_f32_e32 v99, v89, v99
	v_add_f32_e32 v100, v90, v100
	v_add_f32_e32 v101, v91, v101
	v_cvt_pk_bf16_f32 v34, v34, v35
	v_cvt_pk_bf16_f32 v35, v96, v97
	v_cvt_pk_bf16_f32 v98, v98, v99
	v_cvt_pk_bf16_f32 v99, v100, v101
	global_store_dwordx2 v[32:33], v[34:35], off
	global_store_dwordx2 v[32:33], v[98:99], off offset:32
	v_mul_f32_e32 v204, 0x3fb8aa3b, v204
	v_exp_f32_e32 v204, v204
	s_waitcnt lgkmcnt(0)
	v_mul_f32_e32 v28, 0x3fb8aa3b, v205
	v_exp_f32_e32 v28, v28
	v_pk_mul_f32 v[10:11], v[10:11], v[204:205] op_sel_hi:[1,0]
	v_pk_mul_f32 v[8:9], v[8:9], v[204:205] op_sel_hi:[1,0]
	v_pk_mul_f32 v[6:7], v[6:7], v[28:29] op_sel_hi:[1,0]
	v_pk_mul_f32 v[4:5], v[4:5], v[28:29] op_sel_hi:[1,0]
	v_cvt_pk_bf16_f32 v29, v8, s0
	ds_write_b16 v30, v29 offset:23552
	v_cvt_pk_bf16_f32 v29, v9, s0
	ds_write_b16 v30, v29 offset:23696
	v_cvt_pk_bf16_f32 v29, v10, s0
	ds_write_b16 v30, v29 offset:23840
	v_cvt_pk_bf16_f32 v29, v11, s0
	ds_write_b16 v30, v29 offset:23984
	v_cvt_pk_bf16_f32 v29, v4, s0
	ds_write_b16 v31, v29 offset:23584
	v_cvt_pk_bf16_f32 v29, v5, s0
	ds_write_b16 v31, v29 offset:23728
	v_cvt_pk_bf16_f32 v29, v6, s0
	ds_write_b16 v31, v29 offset:23872
	v_cvt_pk_bf16_f32 v29, v7, s0
	ds_write_b16 v31, v29 offset:24016
	s_mov_b64 s[14:15], exec
	s_branch .LBB0_444
.Lgb_m0k2:
	ds_read_b64_tr_b16 v[200:201], v133 offset:18432
	ds_read_b64_tr_b16 v[202:203], v133 offset:18752
	ds_read_b64_tr_b16 v[238:239], v140 offset:9216
	ds_read_b64_tr_b16 v[240:241], v140 offset:9792
	ds_read_b64_tr_b16 v[234:235], v134 offset:18432
	ds_read_b64_tr_b16 v[236:237], v134 offset:18752
	ds_read_b64_tr_b16 v[242:243], v141 offset:9216
	ds_read_b64_tr_b16 v[244:245], v141 offset:9792
	ds_read_b32 v204, v143 offset:32768
	ds_read_b64_tr_b16 v[246:247], v135 offset:9248
	ds_read_b64_tr_b16 v[248:249], v135 offset:9824
	ds_read_b64_tr_b16 v[250:251], v136 offset:9248
	ds_read_b64_tr_b16 v[252:253], v136 offset:9824
	ds_read_b32 v205, v144 offset:32832
	s_movk_i32 s14, 0x90
	v_add_u32_e32 v57, 32, v57
	v_and_b32_e32 v28, 32, v57
	v_mad_u32_u24 v28, v28, s14, v71
	v_lshlrev_b32_e32 v29, 1, v114
	v_lshlrev_b32_e32 v30, 1, v142
	v_add3_u32 v30, v28, v30, v29
	v_lshlrev_b32_e32 v31, 1, v112
	v_add3_u32 v31, v28, v31, v29
	s_waitcnt lgkmcnt(10)
	v_mfma_f32_16x16x32_bf16 v[8:11], v[200:203], v[238:241], v[8:11]
	s_waitcnt lgkmcnt(6)
	v_mfma_f32_16x16x32_bf16 v[8:11], v[234:237], v[242:245], v[8:11]
	s_waitcnt lgkmcnt(3)
	v_mfma_f32_16x16x32_bf16 v[4:7], v[200:203], v[246:249], v[4:7]
	s_waitcnt lgkmcnt(1)
	v_mfma_f32_16x16x32_bf16 v[4:7], v[234:237], v[250:253], v[4:7]
	v_mul_f32_e32 v204, 0x3fb8aa3b, v204
	v_exp_f32_e32 v204, v204
	s_waitcnt lgkmcnt(0)
	v_mul_f32_e32 v28, 0x3fb8aa3b, v205
	v_exp_f32_e32 v28, v28
	s_nop 0
	v_pk_mul_f32 v[10:11], v[10:11], v[204:205] op_sel_hi:[1,0]
	v_pk_mul_f32 v[8:9], v[8:9], v[204:205] op_sel_hi:[1,0]
	s_nop 1
	v_pk_mul_f32 v[6:7], v[6:7], v[28:29] op_sel_hi:[1,0]
	v_pk_mul_f32 v[4:5], v[4:5], v[28:29] op_sel_hi:[1,0]
	v_cvt_pk_bf16_f32 v29, v8, s0
	ds_write_b16 v30, v29 offset:23552
	v_cvt_pk_bf16_f32 v29, v9, s0
	ds_write_b16 v30, v29 offset:23696
	v_cvt_pk_bf16_f32 v29, v10, s0
	ds_write_b16 v30, v29 offset:23840
	v_cvt_pk_bf16_f32 v29, v11, s0
	ds_write_b16 v30, v29 offset:23984
	v_cvt_pk_bf16_f32 v29, v4, s0
	ds_write_b16 v31, v29 offset:23584
	v_cvt_pk_bf16_f32 v29, v5, s0
	ds_write_b16 v31, v29 offset:23728
	v_cvt_pk_bf16_f32 v29, v6, s0
	ds_write_b16 v31, v29 offset:23872
	v_cvt_pk_bf16_f32 v29, v7, s0
	ds_write_b16 v31, v29 offset:24016
	s_mov_b64 s[14:15], exec
	s_branch .LBB0_444
.Lgb_k1:
	s_and_b64 vcc, exec, s[62:63]
	s_cbranch_vccnz .Lgb_m0k1
	ds_read_b128 v[188:191], v132
	ds_read_b128 v[84:87], v33 offset:23552
	ds_read_b128 v[88:91], v33 offset:25856
	ds_read_b128 v[192:195], v132 offset:64
	ds_read_b128 v[92:95], v33 offset:23616
	ds_read_b128 v[196:199], v33 offset:25920
	ds_read_b64_tr_b16 v[200:201], v133 offset:18432
	ds_read_b64_tr_b16 v[202:203], v133 offset:18752
	ds_read_b64_tr_b16 v[238:239], v140 offset:9216
	ds_read_b64_tr_b16 v[240:241], v140 offset:9792
	ds_read_b64_tr_b16 v[234:235], v134 offset:18432
	ds_read_b64_tr_b16 v[236:237], v134 offset:18752
	ds_read_b64_tr_b16 v[242:243], v141 offset:9216
	ds_read_b64_tr_b16 v[244:245], v141 offset:9792
	ds_read_b32 v204, v143 offset:32768
	v_lshlrev_b32_e32 v34, 16, v30
	v_and_b32_e32 v35, 0xffff0000, v30
	v_lshlrev_b32_e32 v96, 16, v31
	v_and_b32_e32 v97, 0xffff0000, v31
	v_lshlrev_b32_e32 v98, 16, v28
	v_and_b32_e32 v99, 0xffff0000, v28
	v_lshlrev_b32_e32 v100, 16, v29
	v_and_b32_e32 v101, 0xffff0000, v29
	v_add_u32_e32 v32, v32, v54
	v_mad_i64_i32 v[32:33], s[14:15], v32, s16, v[2:3]
	s_waitcnt lgkmcnt(12)
	v_mfma_f32_16x16x32_bf16 v[84:87], v[84:87], v[188:191], 0
	v_mfma_f32_16x16x32_bf16 v[88:91], v[88:91], v[188:191], 0
	s_waitcnt lgkmcnt(9)
	v_mfma_f32_16x16x32_bf16 v[84:87], v[92:95], v[192:195], v[84:87]
	v_mfma_f32_16x16x32_bf16 v[88:91], v[196:199], v[192:195], v[88:91]
	s_movk_i32 s14, 0x90
	v_add_u32_e32 v57, 32, v57
	v_and_b32_e32 v28, 32, v57
	v_mad_u32_u24 v28, v28, s14, v71
	v_lshlrev_b32_e32 v29, 1, v114
	v_lshlrev_b32_e32 v30, 1, v142
	v_add3_u32 v30, v28, v30, v29
	s_waitcnt lgkmcnt(5)
	v_mfma_f32_16x16x32_bf16 v[8:11], v[200:203], v[238:241], v[8:11]
	s_waitcnt lgkmcnt(1)
	v_mfma_f32_16x16x32_bf16 v[8:11], v[234:237], v[242:245], v[8:11]
	v_add_f32_e32 v34, v84, v34
	v_add_f32_e32 v35, v85, v35
	v_add_f32_e32 v96, v86, v96
	v_add_f32_e32 v97, v87, v97
	v_add_f32_e32 v98, v88, v98
	v_add_f32_e32 v99, v89, v99
	v_add_f32_e32 v100, v90, v100
	v_add_f32_e32 v101, v91, v101
	v_cvt_pk_bf16_f32 v34, v34, v35
	v_cvt_pk_bf16_f32 v35, v96, v97
	v_cvt_pk_bf16_f32 v98, v98, v99
	v_cvt_pk_bf16_f32 v99, v100, v101
	global_store_dwordx2 v[32:33], v[34:35], off
	global_store_dwordx2 v[32:33], v[98:99], off offset:32
	s_waitcnt lgkmcnt(0)
	v_mul_f32_e32 v204, 0x3fb8aa3b, v204
	v_exp_f32_e32 v204, v204
	s_nop 0
	v_pk_mul_f32 v[10:11], v[10:11], v[204:205] op_sel_hi:[1,0]
	v_pk_mul_f32 v[8:9], v[8:9], v[204:205] op_sel_hi:[1,0]
	v_cvt_pk_bf16_f32 v29, v8, s0
	ds_write_b16 v30, v29 offset:23552
	v_cvt_pk_bf16_f32 v29, v9, s0
	ds_write_b16 v30, v29 offset:23696
	v_cvt_pk_bf16_f32 v29, v10, s0
	ds_write_b16 v30, v29 offset:23840
	v_cvt_pk_bf16_f32 v29, v11, s0
	ds_write_b16 v30, v29 offset:23984
	s_mov_b64 s[14:15], exec
	s_branch .LBB0_444
.Lgb_m0k1:
	ds_read_b64_tr_b16 v[200:201], v133 offset:18432
	ds_read_b64_tr_b16 v[202:203], v133 offset:18752
	ds_read_b64_tr_b16 v[238:239], v140 offset:9216
	ds_read_b64_tr_b16 v[240:241], v140 offset:9792
	ds_read_b64_tr_b16 v[234:235], v134 offset:18432
	ds_read_b64_tr_b16 v[236:237], v134 offset:18752
	ds_read_b64_tr_b16 v[242:243], v141 offset:9216
	ds_read_b64_tr_b16 v[244:245], v141 offset:9792
	ds_read_b32 v204, v143 offset:32768
	s_movk_i32 s14, 0x90
	v_add_u32_e32 v57, 32, v57
	v_and_b32_e32 v28, 32, v57
	v_mad_u32_u24 v28, v28, s14, v71
	v_lshlrev_b32_e32 v29, 1, v114
	v_lshlrev_b32_e32 v30, 1, v142
	v_add3_u32 v30, v28, v30, v29
	s_waitcnt lgkmcnt(5)
	v_mfma_f32_16x16x32_bf16 v[8:11], v[200:203], v[238:241], v[8:11]
	s_waitcnt lgkmcnt(1)
	v_mfma_f32_16x16x32_bf16 v[8:11], v[234:237], v[242:245], v[8:11]
	s_waitcnt lgkmcnt(0)
	v_mul_f32_e32 v204, 0x3fb8aa3b, v204
	v_exp_f32_e32 v204, v204
	s_nop 0
	s_nop 5
	v_pk_mul_f32 v[10:11], v[10:11], v[204:205] op_sel_hi:[1,0]
	v_pk_mul_f32 v[8:9], v[8:9], v[204:205] op_sel_hi:[1,0]
	v_cvt_pk_bf16_f32 v29, v8, s0
	ds_write_b16 v30, v29 offset:23552
	v_cvt_pk_bf16_f32 v29, v9, s0
	ds_write_b16 v30, v29 offset:23696
	v_cvt_pk_bf16_f32 v29, v10, s0
	ds_write_b16 v30, v29 offset:23840
	v_cvt_pk_bf16_f32 v29, v11, s0
	ds_write_b16 v30, v29 offset:23984
	s_mov_b64 s[14:15], exec
	s_branch .LBB0_444
